# v22 + static s_setprio 1 for waves 0-3 on the phase 8 K-loop (flips deleted)
# baseline (speedup 1.0000x reference)
;     __device__ __forceinline__ bool next(int i, Unit& u) const { if (i != 0 || c >= n) return false; u.pm = 0; u.pn = c; u.kt0 = 0; u.nkt = ntk; u.piece = -1; return true; }
; template <class Epi, class Sched>
; __device__ __forceinline__ void gemm_phase(LAS unsigned char* lds, const Gemm g, const Sched& S, const Epi& E) {
;     ...
;         const bool has_next = S.next(ui + 1, nxt);
;         const char* nA = has_next ? (const char*)g.A + (size_t)nxt.pm * tstepA + (size_t)nxt.pn * g.a_pn_off + (size_t)nxt.kt0 * kstep : cA; const char* nB = has_next ? (const char*)g.Bt + (size_t)nxt.pn * tstepB + (size_t)nxt.kt0 * kstep : cB;
;     ...
; #pragma unroll
;         for (int a = 0; a < 2; ++a)
; #pragma unroll
;             for (int b = 0; b < 2; ++b)
; #pragma unroll
;                 for (int m = 0; m < 4; ++m)
; #pragma unroll
;                     for (int n = 0; n < 2; ++n) acc[a][b][m][n] = (f32x4){0.f, 0.f, 0.f, 0.f};
;         cur = nxt; cA = nA; cB = nB; ++ui;
.LBB0_1384:
	s_ashr_i32 s19, s18, 31
	v_cmp_lt_i64_e32 vcc, s[20:21], v[76:77]
	s_lshl_b64 s[20:21], s[18:19], 19
	s_add_u32 s20, s30, s20
	s_addc_u32 s21, s31, s21
	s_and_b64 s[22:23], vcc, exec
	s_cselect_b32 s19, s21, s27
	s_cselect_b32 s52, s20, s26
	s_ashr_i32 s17, s16, 31
	s_lshl_b64 s[22:23], s[16:17], 19
	s_add_u32 s22, s34, s22
	s_addc_u32 s23, s35, s23
	s_and_b64 s[54:55], vcc, exec
	s_cselect_b32 s17, s23, s29
	s_cselect_b32 s53, s22, s28
	s_add_u32 s26, s26, 0x880
	s_addc_u32 s27, s27, 0
	s_add_u32 s28, s28, 0x100
	v_mov_b32_e32 v0, 0
	s_addc_u32 s29, s29, 0
	s_mov_b32 s54, -2
	v_mov_b32_e32 v1, v0
	v_mov_b32_e32 v2, v0
	v_mov_b32_e32 v3, v0
	v_mov_b32_e32 v8, v0
	v_mov_b32_e32 v9, v0
	v_mov_b32_e32 v10, v0
	v_mov_b32_e32 v11, v0
	v_mov_b32_e32 v16, v0
	v_mov_b32_e32 v17, v0
	v_mov_b32_e32 v18, v0
	v_mov_b32_e32 v19, v0
	v_mov_b32_e32 v24, v0
	v_mov_b32_e32 v25, v0
	v_mov_b32_e32 v26, v0
	v_mov_b32_e32 v27, v0
	v_mov_b32_e32 v32, v0
	v_mov_b32_e32 v33, v0
	v_mov_b32_e32 v34, v0
	v_mov_b32_e32 v35, v0
	v_mov_b32_e32 v36, v0
	v_mov_b32_e32 v37, v0
	v_mov_b32_e32 v38, v0
	v_mov_b32_e32 v39, v0
	v_mov_b32_e32 v48, v0
	v_mov_b32_e32 v49, v0
	v_mov_b32_e32 v50, v0
	v_mov_b32_e32 v51, v0
	v_mov_b32_e32 v52, v0
	v_mov_b32_e32 v53, v0
	v_mov_b32_e32 v54, v0
	v_mov_b32_e32 v55, v0
	v_mov_b32_e32 v4, v0
	v_mov_b32_e32 v5, v0
	v_mov_b32_e32 v6, v0
	v_mov_b32_e32 v7, v0
	v_mov_b32_e32 v12, v0
	v_mov_b32_e32 v13, v0
	v_mov_b32_e32 v14, v0
	v_mov_b32_e32 v15, v0
	v_mov_b32_e32 v20, v0
	v_mov_b32_e32 v21, v0
	v_mov_b32_e32 v22, v0
	v_mov_b32_e32 v23, v0
	v_mov_b32_e32 v28, v0
	v_mov_b32_e32 v29, v0
	v_mov_b32_e32 v30, v0
	v_mov_b32_e32 v31, v0
	v_mov_b32_e32 v40, v0
	v_mov_b32_e32 v41, v0
	v_mov_b32_e32 v42, v0
	v_mov_b32_e32 v43, v0
	v_mov_b32_e32 v44, v0
	v_mov_b32_e32 v45, v0
	v_mov_b32_e32 v46, v0
	v_mov_b32_e32 v47, v0
	v_mov_b32_e32 v56, v0
	v_mov_b32_e32 v57, v0
	v_mov_b32_e32 v58, v0
	v_mov_b32_e32 v59, v0
	v_mov_b32_e32 v60, v0
	v_mov_b32_e32 v61, v0
	v_mov_b32_e32 v62, v0
	v_mov_b32_e32 v63, v0
	s_mov_b32 s62, s63
	s_lshr_b32 s72, s3, 8
	s_cmp_lg_u32 s72, 0
	s_cbranch_scc1 .Lprio_1385
	s_setprio 1
